# w_in GEMM row statistics fetched one tile ahead in the previous epilogue, on top of the combined micro-patch build
# speedup vs baseline: 1.0161x; 1.0033x over previous
; #define PG8_STAGE(bufoff, gbase, voff) do { _Pragma("unroll") for (int _i = 0; _i < 2; ++_i) \
;         __builtin_amdgcn_global_load_lds((const unsigned*)((const char*)(gbase) + (voff)[_i]), (LAS unsigned*)(lds + (bufoff) + ldsw + _i * 8192), 16, 0, 0); } while (0)
; #define PG8_WAIT_V(n) asm volatile("s_waitcnt vmcnt(" #n ")" ::: "memory")
; #define PG8_BAR __builtin_amdgcn_s_barrier()
; template <class Epi, bool HALFM = false>
; DI void gemm_phase(LAS unsigned char* lds, const Gemm g, const StaticOrder& S, const Epi& E) {
;     ...
;     const char* cA = (const char*)g.A + (size_t)cur.pm * tstepA; const char* cB = (const char*)g.Bt + (size_t)cur.pn * tstepB;
;     PG8_STAGE(PG8_SB(0, 0), cB, voffB); PG8_STAGE(PG8_SB(0, 1), cB + hstepB, voffB); PG8_STAGE(PG8_SA(0, 0), cA, voffA); PG8_STAGE(PG8_SA(0, 1), cA + hstepA, voffA);
;     if (wr == 1) PG8_BAR;
;     PG8_WAIT_V(2); PG8_BAR;
;     PG8_STAGE(PG8_SB(1, 0), cB + kstep, voffB); PG8_STAGE(PG8_SA(1, 0), cA + kstep, voffA); PG8_STAGE(PG8_SB(1, 1), cB + hstepB + kstep, voffB);
;     PG8_WAIT_V(6); PG8_BAR;
;     DI void operator()(const f32x4 (&acc)[2][2][4][2], const Unit& u, int wr, int wc, int fr, int fq) const {
;         const int row0 = u.pm * BM + wr * 64 + fr, col0 = u.pn * BM + wc * 32 + 8 * fq;
;         float ssv[2][4];
; #pragma unroll
;         for (int ai = 0; ai < 2; ++ai)
; #pragma unroll
;             for (int m = 0; m < 4; ++m) ssv[ai][m] = ss ? ss[row0 + ai * HALF + m * 16] : 0.f;
.LBB0_427:
	s_and_b32 s8, s4, 3
	s_lshl_b32 s59, s1, 6
	s_lshl_b32 s1, s1, 13
	s_lshl_b32 s60, s8, 5
	s_lshl_b32 s9, s8, 12
	v_readlane_b32 s4, v254, 28
	v_readlane_b32 s12, v254, 49
	v_readlane_b32 s5, v254, 29
	s_add_u32 s4, s12, s4
	v_readlane_b32 s12, v254, 50
	s_addc_u32 s5, s12, s5
	v_readlane_b32 s12, v254, 40
	v_readlane_b32 s13, v254, 41
	s_add_u32 s26, s4, s12
	s_addc_u32 s27, s5, s13
	s_cmp_eq_u64 s[4:5], 0
	s_cselect_b64 s[28:29], -1, 0
	s_cmp_lg_u64 s[4:5], 0
	s_cselect_b64 s[30:31], -1, 0
	s_cmp_eq_u64 s[26:27], 0
	s_cselect_b64 s[34:35], -1, 0
	s_add_i32 m0, s55, 0x18000
	v_lshl_add_u64 v[8:9], v[8:9], 0, s[2:3]
	global_load_lds_dwordx4 v[8:9], off
	v_lshl_add_u64 v[6:7], v[6:7], 0, s[2:3]
	s_add_i32 m0, s55, 0x1a000
	s_add_i32 s61, s55, 0x8000
	s_add_i32 s62, s55, 0xa000
	global_load_lds_dwordx4 v[6:7], off
	v_lshl_add_u64 v[2:3], v[2:3], 0, s[2:3]
	s_mov_b32 m0, s61
	s_add_u32 s4, s10, 0x40080
	global_load_lds_dwordx4 v[2:3], off
	v_lshl_add_u64 v[2:3], v[4:5], 0, s[2:3]
	s_mov_b32 m0, s62
	s_addc_u32 s5, s11, 0
	global_load_lds_dwordx4 v[2:3], off
	s_add_i32 m0, s55, 0x1c000
	v_lshl_add_u64 v[2:3], s[4:5], 0, v[0:1]
	global_load_lds_dwordx4 v[2:3], off
	v_lshl_add_u64 v[2:3], s[4:5], 0, v[130:131]
	s_add_i32 m0, s55, 0x1e000
	s_movk_i32 s4, 0x3c0
	global_load_lds_dwordx4 v[2:3], off
	s_waitcnt vmcnt(8)
	s_barrier
	v_and_b32_e32 v2, 48, v10
	v_lshlrev_b32_e32 v3, 6, v10
	v_and_or_b32 v2, v3, s4, v2
	v_lshlrev_b32_e32 v3, 2, v10
	v_and_b32_e32 v3, 32, v3
	v_bitop3_b32 v4, v2, s1, v3 bitop3:0xde
	v_bitop3_b32 v148, v2, s9, v3 bitop3:0xde
	v_lshlrev_b32_e32 v2, 14, v15
	v_and_b32_e32 v2, 0xffff8000, v2
	v_lshl_add_u32 v2, v14, 11, v2
	v_and_b32_e32 v3, 1, v15
	v_lshl_or_b32 v2, v3, 6, v2
	v_lshl_add_u32 v136, v16, 1, v2
	v_lshlrev_b32_e32 v2, 14, v11
	v_and_b32_e32 v2, 0xffff8000, v2
	s_waitcnt vmcnt(6)
	s_cmpk_lt_u32 s0, 0x100
	v_lshl_add_u32 v2, v12, 11, v2
	v_and_b32_e32 v3, 1, v11
	s_cselect_b64 s[36:37], -1, 0
	s_cmp_eq_u32 s8, 0
	v_lshl_or_b32 v2, v3, 6, v2
	v_readlane_b32 s4, v253, 45
	s_mov_b32 s63, 0
	s_cselect_b64 s[38:39], -1, 0
	v_mov_b32_e32 v137, v1
	v_lshl_add_u32 v138, v13, 1, v2
	v_mov_b32_e32 v139, v1
	v_add_u32_e32 v149, 0x100, v4
	v_readlane_b32 s0, v253, 29
	s_mov_b32 s1, s4
	s_barrier
	v_readlane_b32 s5, v253, 46
	s_lshl_b32 s98, s1, 8
	s_add_i32 s98, s98, s59
	v_and_or_b32 v222, v202, 15, s98
	v_ashrrev_i32_e32 v223, 31, v222
	v_lshl_add_u64 v[222:223], v[222:223], 2, s[26:27]
	global_load_dword v224, v[222:223], off
	global_load_dword v225, v[222:223], off offset:64
	global_load_dword v226, v[222:223], off offset:128
	global_load_dword v227, v[222:223], off offset:192
	global_load_dword v228, v[222:223], off offset:512
	global_load_dword v229, v[222:223], off offset:576
	global_load_dword v230, v[222:223], off offset:640
	global_load_dword v231, v[222:223], off offset:704
	s_branch .LBB0_430

;     DI void operator()(const f32x4 (&acc)[2][2][4][2], const Unit& u, int wr, int wc, int fr, int fq) const {
;         const int row0 = u.pm * BM + wr * 64 + fr, col0 = u.pn * BM + wc * 32 + 8 * fq;
;         float ssv[2][4];
; #pragma unroll
;         for (int ai = 0; ai < 2; ++ai)
; #pragma unroll
;             for (int m = 0; m < 4; ++m) ssv[ai][m] = ss ? ss[row0 + ai * HALF + m * 16] : 0.f;
; #pragma unroll
;         for (int ai = 0; ai < 2; ++ai)
; #pragma unroll
;             for (int m = 0; m < 4; ++m) {
;                 const int r = row0 + ai * HALF + m * 16;
;                 const float rs = ss ? __builtin_amdgcn_rsqf(ssv[ai][m] * inv_dim + EPS) : 1.f;
.LBB0_436:
	s_lshl_b32 s1, s1, 8
	v_mov_b32_e32 v144, v202
	s_add_i32 s1, s1, s59
	v_cndmask_b32_e64 v141, 0, 1, s[30:31]
	v_and_or_b32 v140, v144, 15, s1
	v_mov_b32_e32 v157, 0x358637bd
	v_cmp_ne_u32_e64 s[6:7], 1, v141
	s_andn2_b64 vcc, exec, s[30:31]
	v_ashrrev_i32_e32 v141, 31, v140
	v_mov_b32_e32 v145, 0x358637bd
	s_cbranch_vccnz .LBB0_531
	v_fmamk_f32 v145, v224, 0x3a800000, v252
	v_fmamk_f32 v157, v225, 0x3a800000, v252
	v_fmamk_f32 v156, v226, 0x3a800000, v252
	v_fmamk_f32 v155, v227, 0x3a800000, v252
	v_fmamk_f32 v154, v228, 0x3a800000, v252
	v_fmamk_f32 v153, v229, 0x3a800000, v252
	v_fmamk_f32 v152, v230, 0x3a800000, v252
	v_fmamk_f32 v150, v231, 0x3a800000, v252
	s_cmp_eq_u64 s[8:9], 0
	s_cbranch_scc1 .Lsspn_skip
	s_lshl_b32 s98, s42, 8
	s_add_i32 s98, s98, s59
	v_and_or_b32 v222, v202, 15, s98
	v_ashrrev_i32_e32 v223, 31, v222
	v_lshl_add_u64 v[222:223], v[222:223], 2, s[26:27]
	global_load_dword v224, v[222:223], off
	global_load_dword v225, v[222:223], off offset:64
	global_load_dword v226, v[222:223], off offset:128
	global_load_dword v227, v[222:223], off offset:192
	global_load_dword v228, v[222:223], off offset:512
	global_load_dword v229, v[222:223], off offset:576
	global_load_dword v230, v[222:223], off offset:640
	global_load_dword v231, v[222:223], off offset:704
.Lsspn_skip:
	s_branch .LBB0_448
.LBB0_438:
	v_mov_b32_e32 v155, 0x358637bd
	s_and_b64 vcc, exec, s[6:7]
	v_mov_b32_e32 v156, 0x358637bd
	s_cbranch_vccnz .LBB0_533
